# P1 column-section order: gate, ret q, attention q/k/v, ret k/v -- what P2 and the attention blocks read first is written last
# speedup vs baseline: 1.0098x; 1.0098x over previous
; #define PG8_WAIT_V(n) asm volatile("s_waitcnt vmcnt(" #n ")" ::: "memory")
;     __host__ __device__ bool next(int i, Unit& u) const {
;         const long L = (long)i * G + c; if (L >= nwg) return false;
;         int wgid = (int)L; { const int q = nwg / NXCD, r = nwg % NXCD, xcd = wgid % NXCD, off = wgid / NXCD; wgid = (xcd < r ? xcd * (q + 1) : r * (q + 1) + (xcd - r) * q) + off; }
;         const int nig = wgm * nN, gid = wgid / nig, fm = gid * wgm, gsz = (nM - fm) < wgm ? (nM - fm) : wgm;
;         u.pm = fm + ((wgid % nig) % gsz); u.pn = (wgid % nig) / gsz; return true;
; template <class Epi, class Sched, bool ALIGN_EPI = false, bool SP2 = false>
; __device__ __forceinline__ void gemm_phase(PG8_LAS unsigned char* lds, const Gemm g, const Sched& S, const Epi& E) {
;     ...
;     const int tid = tid_, wid = __builtin_amdgcn_readfirstlane(tid >> 6), lane = tid & 63, wr = wid >> 2, wc = wid & 3, fr = lane & 15, fq = lane >> 4;
;     const int K = g.K, nt = K / BK;
;     unsigned voffA[2], voffB[2];
; #pragma unroll
;     for (int i = 0; i < 2; ++i) { int R, C; stage_rc(tid * 16 + i * 8192, R, C); const int Rb = Epi::PERM ? ((R & ~31) + perm32(R & 31)) : R;
;         voffA[i] = (unsigned)(R * K + C) * 2u; voffB[i] = (unsigned)(Rb * K + C) * 2u; }
;     const size_t kstep = (size_t)(BK * 2);
;     const size_t hstep = (size_t)HALF * K * 2;
;     const size_t tstep = 2 * hstep;
;     const unsigned ldsw = (unsigned)wid * 1024u;
;     const int aoff = lds_byte(wr * 64 + fr, fq * 8), boff = lds_byte(wc * 32 + fr, fq * 8);
;     ...
;     Unit cur, nxt; int ui = 0;
;     if (!S.next(0, cur)) return;
;     f32x4 acc[2][2][4][2];
; #pragma unroll
;     for (int a = 0; a < 2; ++a)
; #pragma unroll
;         for (int b = 0; b < 2; ++b)
; #pragma unroll
;             for (int m = 0; m < 4; ++m)
; #pragma unroll
;                 for (int n = 0; n < 2; ++n) acc[a][b][m][n] = (f32x4){0.f, 0.f, 0.f, 0.f};
;     bf16x8 At[4][2], B0[2][2], B1[2][2];
;     const char* cA = (const char*)g.A + (size_t)cur.pm * tstep; const char* cB = (const char*)g.Bt + (size_t)cur.pn * tstep;
;     S.a_ready(cur);
;     if constexpr (SP2) {
;         PG8_STAGE(PG8_SB(0, 0), cB, voffB); PG8_STAGE(PG8_SB(0, 1), cB + hstep, voffB); PG8_STAGE(PG8_SA(0, 0), cA, voffA); PG8_STAGE(PG8_SA(0, 1), cA + hstep, voffA);
;         if (wr == 1) PG8_BAR;
;         PG8_WAIT_V(2); PG8_BAR;
.LBB0_80:
	v_readlane_b32 s4, v244, 10
	v_readlane_b32 s5, v244, 11
	s_cmp_lt_i32 s4, 2
	s_cselect_b64 s[4:5], -1, 0
	s_add_u32 s6, s76, 0x1d00000
	s_addc_u32 s7, s77, 0
	v_writelane_b32 v244, s6, 29
	s_nop 1
	v_writelane_b32 v244, s7, 30
	s_add_u32 s6, s76, 0x2500000
	s_addc_u32 s7, s77, 0
	s_add_u32 s72, s76, 0x5100000
	s_addc_u32 s73, s77, 0
	s_add_u32 s60, s76, 0x6800000
	s_addc_u32 s61, s77, 0
	v_writelane_b32 v244, s6, 31
	s_add_u32 s84, s76, 0xa800000
	s_addc_u32 s85, s77, 0
	v_writelane_b32 v244, s7, 32
	s_and_b64 s[0:1], s[4:5], s[0:1]
	v_writelane_b32 v244, s0, 33
	s_andn2_b64 vcc, exec, s[0:1]
	s_nop 0
	v_writelane_b32 v244, s1, 34
	s_cbranch_vccnz .LBB0_154
	v_writelane_b32 v253, s4, 0
	v_writelane_b32 v253, s5, 1
	v_writelane_b32 v253, s6, 2
	v_writelane_b32 v253, s7, 3
	v_writelane_b32 v253, s8, 4
	v_writelane_b32 v253, s9, 5
	v_writelane_b32 v253, s10, 6
	v_writelane_b32 v253, s11, 7
	v_writelane_b32 v253, s12, 8
	v_writelane_b32 v253, s13, 9
	v_writelane_b32 v253, s14, 10
	v_writelane_b32 v253, s15, 11
	v_writelane_b32 v253, s16, 12
	v_writelane_b32 v253, s17, 13
	v_writelane_b32 v253, s18, 14
	v_writelane_b32 v253, s19, 15
	v_writelane_b32 v253, s20, 16
	v_writelane_b32 v253, s21, 17
	v_writelane_b32 v253, s22, 18
	v_writelane_b32 v253, s23, 19
	v_writelane_b32 v253, s24, 20
	v_writelane_b32 v253, s25, 21
	v_writelane_b32 v253, s26, 22
	v_writelane_b32 v253, s27, 23
	v_writelane_b32 v253, s28, 24
	v_writelane_b32 v253, s29, 25
	v_writelane_b32 v253, s30, 26
	v_writelane_b32 v253, s31, 27
	v_writelane_b32 v253, s32, 28
	v_writelane_b32 v253, s33, 29
	v_writelane_b32 v253, s34, 30
	v_writelane_b32 v253, s35, 31
	v_writelane_b32 v253, s36, 32
	v_writelane_b32 v253, s37, 33
	v_writelane_b32 v253, s38, 34
	v_writelane_b32 v253, s39, 35
	v_writelane_b32 v253, s40, 36
	v_writelane_b32 v253, s41, 37
	v_writelane_b32 v253, s42, 38
	v_writelane_b32 v253, s43, 39
	v_writelane_b32 v253, s44, 40
	v_writelane_b32 v253, s45, 41
	v_writelane_b32 v253, s46, 42
	v_writelane_b32 v253, s47, 43
	v_writelane_b32 v253, s48, 44
	v_writelane_b32 v253, s49, 45
	v_writelane_b32 v253, s50, 46
	v_writelane_b32 v253, s51, 47
	v_writelane_b32 v253, s52, 48
	v_writelane_b32 v253, s53, 49
	v_writelane_b32 v253, s54, 50
	v_writelane_b32 v253, s55, 51
	v_writelane_b32 v253, s56, 52
	v_writelane_b32 v253, s57, 53
	v_writelane_b32 v253, s58, 54
	v_writelane_b32 v253, s59, 55
	s_mov_b32 s40, vcc_lo
	s_mov_b32 s41, vcc_hi
	v_writelane_b32 v253, s40, 60
	v_writelane_b32 v253, s41, 61
	v_lshrrev_b32_e32 v254, 6, v185
	v_readlane_b32 s14, v244, 4
	v_readfirstlane_b32 s36, v254
	s_nop 3
	s_lshr_b32 s37, s36, 2
	s_and_b32 s38, s36, 3
	s_lshl_b32 s35, s36, 10
	s_add_u32 s10, s76, 0x6800000
	s_addc_u32 s11, s77, 0
	s_add_u32 s12, s76, 0x100000
	s_addc_u32 s13, s77, 0
	v_readlane_b32 s6, v244, 28
	s_lshl_b32 s7, s14, 3
	s_mov_b32 s16, 0
	s_mul_i32 s40, s16, s14
	s_add_u32 s40, s40, s2
	s_cmp_lt_u32 s40, 1792
	s_cselect_b32 s44, 1, 0
	s_min_u32 s40, s40, 1791
	s_and_b32 s41, s40, 7
	s_lshr_b32 s42, s40, 3
	s_mul_i32 s41, s41, 224
	s_add_u32 s41, s41, s42
	s_mul_hi_u32 s42, s41, 0x124924a
	s_mul_i32 s43, s42, 224
	s_sub_u32 s43, s41, s43
	s_and_b32 s40, s43, 7
	s_lshl_b32 s42, s42, 3
	s_add_u32 s17, s42, s40
	s_lshr_b32 s18, s43, 3
	s_lshr_b32 s40, s18, 2
	s_lshl_b32 s40, s40, 2
	s_lshr_b32 s41, 0x5421036, s40
	s_and_b32 s41, s41, 7
	s_and_b32 s18, s18, 3
	s_lshl_b32 s41, s41, 2
	s_or_b32 s18, s18, s41
	s_cmp_eq_u32 s44, 0
	s_cbranch_scc1 .Lp1_exit
	v_and_b32_e32 v254, 63, v185
	v_and_b32_e32 v255, 15, v254
	v_lshrrev_b32_e32 v186, 1, v255
	v_lshrrev_b32_e32 v187, 4, v254
	v_xor_b32_e32 v186, v186, v187
	v_lshlrev_b32_e32 v255, 7, v255
	v_lshl_or_b32 v255, v186, 4, v255
	s_lshl_b32 s40, s37, 13
	s_lshl_b32 s41, s38, 12
	s_add_u32 s41, s41, 0x10000
	v_add_u32_e32 v245, s40, v255
	v_add_u32_e32 v247, s41, v255
	v_xor_b32_e32 v246, 64, v245
	v_xor_b32_e32 v248, 64, v247
	v_lshrrev_b32_e32 v255, 3, v254
	v_and_b32_e32 v186, 7, v254
	s_and_b32 s40, s36, 1
	s_lshl_b32 s40, s40, 2
	v_lshrrev_b32_e32 v187, 1, v255
	v_add_u32_e32 v187, s40, v187
	v_xor_b32_e32 v186, v186, v187
	v_lshlrev_b32_e32 v186, 4, v186
	s_lshl_b32 s40, s36, 3
	v_add_u32_e32 v187, s40, v255
	v_mul_u32_u24_e32 v187, 0x1000, v187
	v_add_u32_e32 v249, v187, v186
	v_add_u32_e32 v250, 0x40000, v249
	s_and_b32 s40, s36, 3
	s_lshl_b32 s40, s40, 3
	v_add_u32_e32 v187, s40, v255
	v_lshrrev_b32_e32 v254, 4, v187
	v_lshlrev_b32_e32 v254, 2, v254
	v_and_b32_e32 v255, 3, v187
	v_add_u32_e32 v254, v254, v255
	v_and_b32_e32 v187, 12, v187
	v_lshl_add_u32 v254, v187, 1, v254
	s_lshr_b32 s40, s36, 2
	s_lshl_b32 s40, s40, 5
	v_add_u32_e32 v254, s40, v254
	v_mul_u32_u24_e32 v254, 0x1000, v254
	v_add_u32_e32 v251, v254, v186
	v_add_u32_e32 v252, 0x40000, v251
	s_mul_i32 s40, s17, 0x100000
	s_add_u32 s22, s10, s40
	s_addc_u32 s23, s11, 0
	s_mul_i32 s40, s18, 0x100000
	s_add_u32 s24, s12, s40
	s_addc_u32 s25, s13, 0
	s_and_b32 s40, s16, 1
	s_lshl_b32 s4, s40, 8
	s_sub_u32 s4, 128, s4
	s_sub_u32 s5, 0, s40
	s_mul_i32 s8, s40, 3968
	s_add_u32 s30, s22, s8
	s_addc_u32 s31, s23, 0
	s_add_u32 s32, s24, s8
	s_addc_u32 s33, s25, 0
	s_add_u32 s56, s30, 0x80000
	s_addc_u32 s57, s31, 0
	s_add_u32 s58, s32, 0x80000
	s_addc_u32 s59, s33, 0
	s_add_i32 m0, s35, 0x0
	s_nop 0
	global_load_lds_dwordx4 v249, s[30:31]
	s_add_i32 m0, s35, 0x2000
	s_nop 0
	global_load_lds_dwordx4 v250, s[30:31]
	s_add_i32 m0, s35, 0x10000
	s_nop 0
	global_load_lds_dwordx4 v251, s[32:33]
	s_add_i32 m0, s35, 0x12000
	s_nop 0
	global_load_lds_dwordx4 v252, s[32:33]
	s_add_i32 m0, s35, 0x4000
	s_nop 0
	global_load_lds_dwordx4 v249, s[56:57]
	s_add_i32 m0, s35, 0x6000
	s_nop 0
	global_load_lds_dwordx4 v250, s[56:57]
	s_add_i32 m0, s35, 0x14000
	s_nop 0
	global_load_lds_dwordx4 v251, s[58:59]
	s_add_i32 m0, s35, 0x16000
	s_nop 0
	global_load_lds_dwordx4 v252, s[58:59]
	s_add_u32 s30, s30, s4
	s_addc_u32 s31, s31, s5
	s_add_u32 s56, s56, s4
	s_addc_u32 s57, s57, s5
	s_add_u32 s32, s32, s4
	s_addc_u32 s33, s33, s5
	s_add_u32 s58, s58, s4
	s_addc_u32 s59, s59, s5
	s_add_i32 m0, s35, 0x8000
	s_nop 0
	global_load_lds_dwordx4 v249, s[30:31]
	s_add_i32 m0, s35, 0xa000
	s_nop 0
	global_load_lds_dwordx4 v250, s[30:31]
	s_add_i32 m0, s35, 0x1c000
	s_nop 0
	global_load_lds_dwordx4 v251, s[58:59]
	s_add_i32 m0, s35, 0x1e000
	s_nop 0
	global_load_lds_dwordx4 v252, s[58:59]
	s_add_i32 m0, s35, 0xc000
	s_nop 0
	global_load_lds_dwordx4 v249, s[56:57]
	s_add_i32 m0, s35, 0xe000
	s_nop 0
	global_load_lds_dwordx4 v250, s[56:57]
	s_add_i32 m0, s35, 0x18000
	s_nop 0
	global_load_lds_dwordx4 v251, s[32:33]
	s_add_i32 m0, s35, 0x1a000
	s_nop 0
	global_load_lds_dwordx4 v252, s[32:33]
	s_add_u32 s30, s30, s4
	s_addc_u32 s31, s31, s5
	s_add_u32 s56, s56, s4
	s_addc_u32 s57, s57, s5
	s_add_u32 s32, s32, s4
	s_addc_u32 s33, s33, s5
	s_add_u32 s58, s58, s4
	s_addc_u32 s59, s59, s5
	s_waitcnt vmcnt(12)
	s_barrier
; #define PG8_STAGE(bufoff, gbase, voff) do { _Pragma("unroll") for (int _i = 0; _i < 2; ++_i) \
;         __builtin_amdgcn_global_load_lds((const unsigned*)((const char*)(gbase) + (voff)[_i]), (PG8_LAS unsigned*)(lds + (bufoff) + ldsw + _i * 8192), 16, 0, 0); } while (0)
; #define PG8_LDA(dst, b, h) do { _Pragma("unroll") for (int m = 0; m < 4; ++m) _Pragma("unroll") for (int k = 0; k < 2; ++k) dst[m][k] = *(const PG8_LAS bf16x8*)(lds + PG8_SA(b, h) + aoff + m * 2048 + k * 1024); } while (0)
; #define PG8_LDB(dst, b, h) do { _Pragma("unroll") for (int n = 0; n < 2; ++n) _Pragma("unroll") for (int k = 0; k < 2; ++k) dst[n][k] = *(const PG8_LAS bf16x8*)(lds + PG8_SB(b, h) + boff + n * 2048 + k * 1024); } while (0)
; #define PG8_SCHED __builtin_amdgcn_sched_barrier(0)
; template <class Epi, class Sched, bool ALIGN_EPI = false, bool SP2 = false>
; __device__ __forceinline__ void gemm_phase(PG8_LAS unsigned char* lds, const Gemm g, const Sched& S, const Epi& E) {
;     ...
;     f32x4 acc[2][2][4][2];
; #pragma unroll
;     for (int a = 0; a < 2; ++a)
; #pragma unroll
;         for (int b = 0; b < 2; ++b)
; #pragma unroll
;             for (int m = 0; m < 4; ++m)
; #pragma unroll
;                 for (int n = 0; n < 2; ++n) acc[a][b][m][n] = (f32x4){0.f, 0.f, 0.f, 0.f};
;     ...
;         const bool has_next = S.next(ui + 1, nxt);
;         const char* nA = has_next ? (const char*)g.A + (size_t)nxt.pm * tstep : cA; const char* nB = has_next ? (const char*)g.Bt + (size_t)nxt.pn * tstep : cB;
;         for (int t = 0; t < nt; t += 2) {
;             const bool last = (t == nt - 2);
;             const char* a1 = cA + (size_t)(t + 1) * kstep;
;             const char* a2 = last ? nA : cA + (size_t)(t + 2) * kstep; const char* b2 = last ? nB : cB + (size_t)(t + 2) * kstep;
;             const char* a3 = a2 + kstep; const char* b3 = b2 + kstep;
;             if (last && has_next) S.a_ready(nxt);
;             if constexpr (SP2) {
;             PG8_LDB(B0, 0, 0); PG8_LDB(B1, 0, 1); PG8_SCHED; PG8_LDA(At, 0, 0); PG8_STAGE(PG8_SA(1, 1), a1 + hstep, voffA);
.Lp1_unit:
	s_add_u32 s45, s16, 1
	s_mul_i32 s40, s45, s14
	s_add_u32 s40, s40, s2
	s_cmp_lt_u32 s40, 1792
	s_cselect_b32 s19, 1, 0
	s_min_u32 s40, s40, 1791
	s_and_b32 s41, s40, 7
	s_lshr_b32 s42, s40, 3
	s_mul_i32 s41, s41, 224
	s_add_u32 s41, s41, s42
	s_mul_hi_u32 s42, s41, 0x124924a
	s_mul_i32 s43, s42, 224
	s_sub_u32 s43, s41, s43
	s_and_b32 s40, s43, 7
	s_lshl_b32 s42, s42, 3
	s_add_u32 s20, s42, s40
	s_lshr_b32 s21, s43, 3
	s_lshr_b32 s40, s21, 2
	s_lshl_b32 s40, s40, 2
	s_lshr_b32 s41, 0x5421036, s40
	s_and_b32 s41, s41, 7
	s_and_b32 s21, s21, 3
	s_lshl_b32 s41, s41, 2
	s_or_b32 s21, s21, s41
	s_mul_i32 s40, s20, 0x100000
	s_add_u32 s26, s10, s40
	s_addc_u32 s27, s11, 0
	s_mul_i32 s40, s21, 0x100000
	s_add_u32 s28, s12, s40
	s_addc_u32 s29, s13, 0
	s_cmp_eq_u32 s19, 0
	s_cselect_b32 s26, s22, s26
	s_cselect_b32 s27, s23, s27
	s_cselect_b32 s28, s24, s28
	s_cselect_b32 s29, s25, s29
	s_add_u32 s30, s22, s8
	s_addc_u32 s31, s23, 0
	s_add_u32 s32, s24, s8
	s_addc_u32 s33, s25, 0
	s_add_u32 s30, s30, s4
	s_addc_u32 s31, s31, s5
	s_add_u32 s32, s32, s4
	s_addc_u32 s33, s33, s5
	s_add_u32 s30, s30, s4
	s_addc_u32 s31, s31, s5
	s_add_u32 s32, s32, s4
	s_addc_u32 s33, s33, s5
	s_add_u32 s56, s30, 0x80000
	s_addc_u32 s57, s31, 0
	s_add_u32 s58, s32, 0x80000
	s_addc_u32 s59, s33, 0
	s_movk_i32 s34, 16
	v_mov_b32_e32 v0, 0
	v_mov_b32_e32 v1, 0
	v_mov_b32_e32 v2, 0
	v_mov_b32_e32 v3, 0
	v_mov_b32_e32 v4, 0
	v_mov_b32_e32 v5, 0
	v_mov_b32_e32 v6, 0
	v_mov_b32_e32 v7, 0
	v_mov_b32_e32 v8, 0
	v_mov_b32_e32 v9, 0
	v_mov_b32_e32 v10, 0
	v_mov_b32_e32 v11, 0
	v_mov_b32_e32 v12, 0
	v_mov_b32_e32 v13, 0
	v_mov_b32_e32 v14, 0
	v_mov_b32_e32 v15, 0
	v_mov_b32_e32 v16, 0
	v_mov_b32_e32 v17, 0
	v_mov_b32_e32 v18, 0
	v_mov_b32_e32 v19, 0
	v_mov_b32_e32 v20, 0
	v_mov_b32_e32 v21, 0
	v_mov_b32_e32 v22, 0
	v_mov_b32_e32 v23, 0
	v_mov_b32_e32 v24, 0
	v_mov_b32_e32 v25, 0
	v_mov_b32_e32 v26, 0
	v_mov_b32_e32 v27, 0
	v_mov_b32_e32 v28, 0
	v_mov_b32_e32 v29, 0
	v_mov_b32_e32 v30, 0
	v_mov_b32_e32 v31, 0
	v_mov_b32_e32 v32, 0
	v_mov_b32_e32 v33, 0
	v_mov_b32_e32 v34, 0
	v_mov_b32_e32 v35, 0
	v_mov_b32_e32 v36, 0
	v_mov_b32_e32 v37, 0
	v_mov_b32_e32 v38, 0
	v_mov_b32_e32 v39, 0
	v_mov_b32_e32 v40, 0
	v_mov_b32_e32 v41, 0
	v_mov_b32_e32 v42, 0
	v_mov_b32_e32 v43, 0
	v_mov_b32_e32 v44, 0
	v_mov_b32_e32 v45, 0
	v_mov_b32_e32 v46, 0
	v_mov_b32_e32 v47, 0
	v_mov_b32_e32 v48, 0
	v_mov_b32_e32 v49, 0
	v_mov_b32_e32 v50, 0
	v_mov_b32_e32 v51, 0
	v_mov_b32_e32 v52, 0
	v_mov_b32_e32 v53, 0
	v_mov_b32_e32 v54, 0
	v_mov_b32_e32 v55, 0
	v_mov_b32_e32 v56, 0
	v_mov_b32_e32 v57, 0
	v_mov_b32_e32 v58, 0
	v_mov_b32_e32 v59, 0
	v_mov_b32_e32 v60, 0
	v_mov_b32_e32 v61, 0
	v_mov_b32_e32 v62, 0
	v_mov_b32_e32 v63, 0
	v_mov_b32_e32 v64, 0
	v_mov_b32_e32 v65, 0
	v_mov_b32_e32 v66, 0
	v_mov_b32_e32 v67, 0
	v_mov_b32_e32 v68, 0
	v_mov_b32_e32 v69, 0
	v_mov_b32_e32 v70, 0
	v_mov_b32_e32 v71, 0
	v_mov_b32_e32 v72, 0
	v_mov_b32_e32 v73, 0
	v_mov_b32_e32 v74, 0
	v_mov_b32_e32 v75, 0
	v_mov_b32_e32 v76, 0
	v_mov_b32_e32 v77, 0
	v_mov_b32_e32 v78, 0
	v_mov_b32_e32 v79, 0
	v_mov_b32_e32 v80, 0
	v_mov_b32_e32 v81, 0
	v_mov_b32_e32 v82, 0
	v_mov_b32_e32 v83, 0
	v_mov_b32_e32 v84, 0
	v_mov_b32_e32 v85, 0
	v_mov_b32_e32 v86, 0
	v_mov_b32_e32 v87, 0
	v_mov_b32_e32 v88, 0
	v_mov_b32_e32 v89, 0
	v_mov_b32_e32 v90, 0
	v_mov_b32_e32 v91, 0
	v_mov_b32_e32 v92, 0
	v_mov_b32_e32 v93, 0
	v_mov_b32_e32 v94, 0
	v_mov_b32_e32 v95, 0
	v_mov_b32_e32 v96, 0
	v_mov_b32_e32 v97, 0
	v_mov_b32_e32 v98, 0
	v_mov_b32_e32 v99, 0
	v_mov_b32_e32 v100, 0
	v_mov_b32_e32 v101, 0
	v_mov_b32_e32 v102, 0
	v_mov_b32_e32 v103, 0
	v_mov_b32_e32 v104, 0
	v_mov_b32_e32 v105, 0
	v_mov_b32_e32 v106, 0
	v_mov_b32_e32 v107, 0
	v_mov_b32_e32 v108, 0
	v_mov_b32_e32 v109, 0
	v_mov_b32_e32 v110, 0
	v_mov_b32_e32 v111, 0
	v_mov_b32_e32 v112, 0
	v_mov_b32_e32 v113, 0
	v_mov_b32_e32 v114, 0
	v_mov_b32_e32 v115, 0
	v_mov_b32_e32 v116, 0
	v_mov_b32_e32 v117, 0
	v_mov_b32_e32 v118, 0
	v_mov_b32_e32 v119, 0
	v_mov_b32_e32 v120, 0
	v_mov_b32_e32 v121, 0
	v_mov_b32_e32 v122, 0
	v_mov_b32_e32 v123, 0
	v_mov_b32_e32 v124, 0
	v_mov_b32_e32 v125, 0
	v_mov_b32_e32 v126, 0
	v_mov_b32_e32 v127, 0
	ds_read_b128 v[196:199], v247 offset:0
	ds_read_b128 v[200:203], v248 offset:0
	ds_read_b128 v[204:207], v247 offset:2048
	ds_read_b128 v[208:211], v248 offset:2048
	ds_read_b128 v[128:131], v245 offset:0
	ds_read_b128 v[132:135], v246 offset:0
	ds_read_b128 v[136:139], v245 offset:2048
	ds_read_b128 v[140:143], v246 offset:2048
	ds_read_b128 v[144:147], v245 offset:4096
	ds_read_b128 v[148:151], v246 offset:4096
	ds_read_b128 v[152:155], v245 offset:6144
	ds_read_b128 v[156:159], v246 offset:6144
	s_cmp_ge_u32 s36, 4
	s_cbranch_scc1 .Lp1_kloop1
